# in-proj and ffn-up phases: workgroups with odd row-tile index start about 16us late (two-group half-unit stagger to de-synchronise epilogue store bursts)
# baseline (speedup 1.0000x reference)
.LBB0_11:
	v_readlane_b32 s100, v253, 6
	s_nop 0
	s_add_i32 s100, s100, -1
	s_cmp_gt_i32 s100, 10
	s_cselect_b32 s101, 11, 0
	s_sub_i32 s100, s100, s101
	s_lshl_b32 s100, 1, s100
	s_and_b32 s100, s100, 0x212
	s_cmp_eq_u32 s100, 0
	s_cbranch_scc1 .Lst_done
	s_bfe_u32 s100, s90, 0x10004
	s_lshl_b32 s100, s100, 2
	s_cmp_eq_u32 s100, 0
	s_cbranch_scc1 .Lst_done
.Lst_loop:
	s_sleep 127
	s_add_i32 s100, s100, -1
	s_cmp_lg_u32 s100, 0
	s_cbranch_scc1 .Lst_loop

	.amdhsa_kernel _Z10fwd_kernel6Params
		.amdhsa_group_segment_fixed_size 0
		.amdhsa_private_segment_fixed_size 0
		.amdhsa_kernarg_size 584
		.amdhsa_user_sgpr_count 2
		.amdhsa_user_sgpr_dispatch_ptr 0
		.amdhsa_user_sgpr_queue_ptr 0
		.amdhsa_user_sgpr_kernarg_segment_ptr 1
		.amdhsa_user_sgpr_dispatch_id 0
		.amdhsa_user_sgpr_kernarg_preload_length 0
		.amdhsa_user_sgpr_kernarg_preload_offset 0
		.amdhsa_user_sgpr_private_segment_size 0
		.amdhsa_uses_dynamic_stack 0
		.amdhsa_enable_private_segment 0
		.amdhsa_system_sgpr_workgroup_id_x 1
		.amdhsa_system_sgpr_workgroup_id_y 0
		.amdhsa_system_sgpr_workgroup_id_z 0
		.amdhsa_system_sgpr_workgroup_info 0
		.amdhsa_system_vgpr_workitem_id 2
		.amdhsa_next_free_vgpr 255
		.amdhsa_next_free_sgpr 102
		.amdhsa_accum_offset 256
		.amdhsa_reserve_vcc 1
		.amdhsa_float_round_mode_32 0
		.amdhsa_float_round_mode_16_64 0
		.amdhsa_float_denorm_mode_32 3
		.amdhsa_float_denorm_mode_16_64 3
		.amdhsa_dx10_clamp 1
		.amdhsa_ieee_mode 1
		.amdhsa_fp16_overflow 0
		.amdhsa_tg_split 0
		.amdhsa_exception_fp_ieee_invalid_op 0
		.amdhsa_exception_fp_denorm_src 0
		.amdhsa_exception_fp_ieee_div_zero 0
		.amdhsa_exception_fp_ieee_overflow 0
		.amdhsa_exception_fp_ieee_underflow 0
		.amdhsa_exception_fp_ieee_inexact 0
		.amdhsa_exception_int_div_zero 0
	.end_amdhsa_kernel

amdhsa.kernels:
  - .agpr_count:     0
    .args:
      - .offset:         0
        .size:           328
        .value_kind:     by_value
      - .offset:         328
        .size:           4
        .value_kind:     hidden_block_count_x
      - .offset:         332
        .size:           4
        .value_kind:     hidden_block_count_y
      - .offset:         336
        .size:           4
        .value_kind:     hidden_block_count_z
      - .offset:         340
        .size:           2
        .value_kind:     hidden_group_size_x
      - .offset:         342
        .size:           2
        .value_kind:     hidden_group_size_y
      - .offset:         344
        .size:           2
        .value_kind:     hidden_group_size_z
      - .offset:         346
        .size:           2
        .value_kind:     hidden_remainder_x
      - .offset:         348
        .size:           2
        .value_kind:     hidden_remainder_y
      - .offset:         350
        .size:           2
        .value_kind:     hidden_remainder_z
      - .offset:         368
        .size:           8
        .value_kind:     hidden_global_offset_x
      - .offset:         376
        .size:           8
        .value_kind:     hidden_global_offset_y
      - .offset:         384
        .size:           8
        .value_kind:     hidden_global_offset_z
      - .offset:         392
        .size:           2
        .value_kind:     hidden_grid_dims
      - .offset:         416
        .size:           8
        .value_kind:     hidden_multigrid_sync_arg
      - .offset:         448
        .size:           4
        .value_kind:     hidden_dynamic_lds_size
    .group_segment_fixed_size: 0
    .kernarg_segment_align: 8
    .kernarg_segment_size: 584
    .language:       OpenCL C
    .language_version:
      - 2
      - 0
    .max_flat_workgroup_size: 512
    .name:           _Z10fwd_kernel6Params
    .private_segment_fixed_size: 0
    .sgpr_count:     108
    .sgpr_spill_count: 222
    .symbol:         _Z10fwd_kernel6Params.kd
    .uniform_work_group_size: 1
    .uses_dynamic_stack: false
    .vgpr_count:     255
    .vgpr_spill_count: 0
    .wavefront_size: 64
